# GU SwiGLU epilogue keeps the row scales (rstd) in registers while the workgroup stays on one row panel: no ssq reload / vmcnt(0) drain per tile
# speedup vs baseline: 1.0195x; 1.0021x over previous
; #define PG8_STAGE(bufoff, gbase, voff) do { _Pragma("unroll") for (int _i = 0; _i < 2; ++_i) \
;         __builtin_amdgcn_global_load_lds((const unsigned*)((const char*)(gbase) + (voff)[_i]), (LAS unsigned*)(lds + (bufoff) + ldsw + _i * 8192), 16, 0, 0); } while (0)
; #define PG8_WAIT_V(n) asm volatile("s_waitcnt vmcnt(" #n ")" ::: "memory")
; #define PG8_BAR __builtin_amdgcn_s_barrier()
; template <class Epi, bool ALIGN_EPI>
; __device__ __forceinline__ void gemm_phase(LAS unsigned char* lds, const Gemm g, const StaticOrder& S, const Epi& E, const int tid) {
;     ...
;     const unsigned ldsw = (unsigned)wid * 1024u;
;     const int aoff = lds_byte(wr * 64 + fr, fq * 8), boff = lds_byte(wc * 32 + fr, fq * 8);
;     ...
;     PG8_WAIT_V(2); PG8_BAR;
;     PG8_STAGE(PG8_SB(1, 0), cB + kstep, voffB); PG8_STAGE(PG8_SA(1, 0), cA + kstep, voffA); PG8_STAGE(PG8_SB(1, 1), cB + hB + kstep, voffB);
;     PG8_WAIT_V(6); PG8_BAR;
.LBB0_297:
	v_lshl_add_u64 v[8:9], v[144:145], 0, v[168:169]
	v_mov_b32_e32 v129, v169
	v_lshl_add_u64 v[10:11], v[144:145], 0, v[128:129]
	v_mov_b32_e32 v133, v169
	s_add_i32 m0, s51, 0x18000
	v_lshl_add_u64 v[8:9], v[8:9], 0, s[92:93]
	v_lshl_add_u64 v[14:15], v[142:143], 0, v[132:133]
	v_mov_b32_e32 v131, v169
	s_waitcnt vmcnt(2)
	s_barrier
	global_load_lds_dwordx4 v[8:9], off
	v_lshl_add_u64 v[8:9], v[10:11], 0, s[92:93]
	s_add_i32 m0, s51, 0x1a000
	s_add_i32 s56, s51, 0x8000
	v_lshl_add_u64 v[16:17], v[142:143], 0, v[130:131]
	global_load_lds_dwordx4 v[8:9], off
	v_lshl_add_u64 v[8:9], v[14:15], 0, s[92:93]
	s_mov_b32 m0, s56
	s_add_i32 s57, s51, 0xa000
	v_lshl_add_u64 v[12:13], v[0:1], 0, v[168:169]
	global_load_lds_dwordx4 v[8:9], off
	v_lshl_add_u64 v[8:9], v[16:17], 0, s[92:93]
	s_mov_b32 m0, s57
	v_lshl_add_u64 v[0:1], v[0:1], 0, v[128:129]
	global_load_lds_dwordx4 v[8:9], off
	s_add_i32 m0, s51, 0x1c000
	v_lshl_add_u64 v[8:9], v[12:13], 0, s[92:93]
	global_load_lds_dwordx4 v[8:9], off
	v_lshl_add_u64 v[0:1], v[0:1], 0, s[92:93]
	s_add_i32 m0, s51, 0x1e000
	v_and_b32_e32 v18, 15, v170
	global_load_lds_dwordx4 v[0:1], off
	v_add_u32_e32 v0, v7, v5
	s_lshr_b32 s55, s1, 6
	v_and_b32_e32 v19, 48, v170
	v_lshlrev_b32_e32 v18, 6, v18
	v_lshlrev_b32_e32 v21, 2, v170
	s_lshl_b32 s9, s9, 12
	v_add_lshl_u32 v0, v0, v6, 1
	v_mov_b32_e32 v1, v169
	v_or_b32_e32 v20, v18, v19
	s_lshl_b32 s10, s10, 13
	v_and_b32_e32 v21, 32, v21
	s_and_b32 s9, s9, 0x3000
	s_waitcnt vmcnt(6)
	s_add_i32 s58, s55, -2
	v_lshl_add_u64 v[134:135], s[94:95], 0, v[0:1]
	v_add_u32_e32 v0, v4, v2
	v_bitop3_b32 v18, v18, v21, v19 bitop3:0x36
	v_bitop3_b32 v19, s10, v20, v21 bitop3:0xf6
	s_cmpk_lt_u32 s8, 0x100
	v_add_lshl_u32 v0, v0, v3, 1
	v_or_b32_e32 v151, s9, v18
	s_cselect_b64 s[42:43], -1, 0
	s_ashr_i32 s59, s6, 31
	s_mov_b32 s39, s95
	v_lshl_add_u64 v[136:137], s[94:95], 0, v[0:1]
	s_mov_b32 s60, 0
	v_add_u32_e32 v153, 0, v19
	s_barrier
	v_mov_b32_e32 v254, -1
	s_branch .LBB0_300

; __device__ __forceinline__ float siluf_(float x) { return x * sigmoidf_(x); }
; __device__ __forceinline__ void load_rstd(float (&rsv)[2][4], const ssq_t* ssq, int row0) {
;     ssq_t t[2][4];
; #pragma unroll
;     for (int ai = 0; ai < 2; ++ai)
; #pragma unroll
;         for (int m = 0; m < 4; ++m) t[ai][m] = ssq[row0 + ai * HALF + m * 16];
; #pragma unroll
;     for (int ai = 0; ai < 2; ++ai)
; #pragma unroll
;         for (int m = 0; m < 4; ++m) rsv[ai][m] = __builtin_amdgcn_rsqf((float)t[ai][m] * (SSQ_INV / 1024.0f) + 1e-6f);
; }
;     __device__ __forceinline__ void operator()(const f32x4 (&acc)[2][2][4][2], const Unit& u, int wr, int wc, int fr, int fq) const {
;         const int row0 = u.pm * BM + wr * 64 + fr, col0 = u.pn * HALF + wc * 32 + 8 * fq;
;         float rsv[2][4]; load_rstd(rsv, ssq, row0);
; #pragma unroll
;         for (int ai = 0; ai < 2; ++ai)
; #pragma unroll
;             for (int m = 0; m < 4; ++m) { const int row = row0 + ai * HALF + m * 16; bf16_t* rowp = O + (size_t)row * ldc + col0; const float rs = rsv[ai][m];
;                 f32x4 v0, v1;
; #pragma unroll
;                 for (int j = 0; j < 4; ++j) { v0[j] = siluf_(acc[ai][0][m][0][j] * rs) * (acc[ai][1][m][0][j] * rs); v1[j] = siluf_(acc[ai][0][m][1][j] * rs) * (acc[ai][1][m][1][j] * rs); }
.LBB0_311:
	v_lshrrev_b32_e32 v150, 8, v170
	v_and_b32_e32 v152, 15, v170
	v_lshl_add_u32 v150, v150, 6, v152
	s_lshl_b32 s10, s64, 8
	v_add_u32_e32 v150, s10, v150
	v_bfe_u32 v152, v170, 6, 2
	v_bfe_u32 v160, v170, 4, 2
	v_lshlrev_b32_e32 v152, 5, v152
	v_lshl_or_b32 v152, v160, 3, v152
	s_lshl_b32 s10, s63, 7
	v_add_u32_e32 v152, s10, v152
	v_mul_lo_u32 v160, v150, s28
	v_add_lshl_u32 v160, v160, v152, 1
	v_readfirstlane_b32 s10, v254
	s_cmp_eq_u32 s10, s64
	s_cbranch_scc1 .Lsw3_cached
	v_lshlrev_b32_e32 v166, 3, v150
	v_mov_b32_e32 v167, 0
	v_lshl_add_u64 v[166:167], v[166:167], 0, s[26:27]
	global_load_dwordx2 v[144:145], v[166:167], off
	global_load_dwordx2 v[146:147], v[166:167], off offset:128
	global_load_dwordx2 v[148:149], v[166:167], off offset:256
	global_load_dwordx2 v[154:155], v[166:167], off offset:384
	global_load_dwordx2 v[156:157], v[166:167], off offset:1024
	global_load_dwordx2 v[158:159], v[166:167], off offset:1152
	global_load_dwordx2 v[162:163], v[166:167], off offset:1280
	global_load_dwordx2 v[164:165], v[166:167], off offset:1408
	s_waitcnt vmcnt(0)
	v_ffbh_u32_e32 v150, v145
	v_min_u32_e32 v150, 32, v150
	v_lshlrev_b64 v[144:145], v150, v[144:145]
	v_min_u32_e32 v144, 1, v144
	v_or_b32_e32 v144, v145, v144
	v_cvt_f32_u32_e32 v144, v144
	v_sub_u32_e32 v150, 32, v150
	v_ldexp_f32 v144, v144, v150
	v_fmamk_f32 v144, v144, 0x30800000, v223
	v_rsq_f32_e32 v144, v144
	v_ffbh_u32_e32 v150, v147
	v_min_u32_e32 v150, 32, v150
	v_lshlrev_b64 v[146:147], v150, v[146:147]
	v_min_u32_e32 v146, 1, v146
	v_or_b32_e32 v146, v147, v146
	v_cvt_f32_u32_e32 v146, v146
	v_sub_u32_e32 v150, 32, v150
	v_ldexp_f32 v146, v146, v150
	v_fmamk_f32 v146, v146, 0x30800000, v223
	v_rsq_f32_e32 v146, v146
	v_ffbh_u32_e32 v150, v149
	v_min_u32_e32 v150, 32, v150
	v_lshlrev_b64 v[148:149], v150, v[148:149]
	v_min_u32_e32 v148, 1, v148
	v_or_b32_e32 v148, v149, v148
	v_cvt_f32_u32_e32 v148, v148
	v_sub_u32_e32 v150, 32, v150
	v_ldexp_f32 v148, v148, v150
	v_fmamk_f32 v148, v148, 0x30800000, v223
	v_rsq_f32_e32 v148, v148
	v_ffbh_u32_e32 v150, v155
	v_min_u32_e32 v150, 32, v150
	v_lshlrev_b64 v[154:155], v150, v[154:155]
	v_min_u32_e32 v154, 1, v154
	v_or_b32_e32 v154, v155, v154
	v_cvt_f32_u32_e32 v154, v154
	v_sub_u32_e32 v150, 32, v150
	v_ldexp_f32 v154, v154, v150
	v_fmamk_f32 v154, v154, 0x30800000, v223
	v_rsq_f32_e32 v154, v154
	v_ffbh_u32_e32 v150, v157
	v_min_u32_e32 v150, 32, v150
	v_lshlrev_b64 v[156:157], v150, v[156:157]
	v_min_u32_e32 v156, 1, v156
	v_or_b32_e32 v156, v157, v156
	v_cvt_f32_u32_e32 v156, v156
	v_sub_u32_e32 v150, 32, v150
	v_ldexp_f32 v156, v156, v150
	v_fmamk_f32 v156, v156, 0x30800000, v223
	v_rsq_f32_e32 v156, v156
	v_ffbh_u32_e32 v150, v159
	v_min_u32_e32 v150, 32, v150
	v_lshlrev_b64 v[158:159], v150, v[158:159]
	v_min_u32_e32 v158, 1, v158
	v_or_b32_e32 v158, v159, v158
	v_cvt_f32_u32_e32 v158, v158
	v_sub_u32_e32 v150, 32, v150
	v_ldexp_f32 v158, v158, v150
	v_fmamk_f32 v158, v158, 0x30800000, v223
	v_rsq_f32_e32 v158, v158
	v_ffbh_u32_e32 v150, v163
	v_min_u32_e32 v150, 32, v150
	v_lshlrev_b64 v[162:163], v150, v[162:163]
	v_min_u32_e32 v162, 1, v162
	v_or_b32_e32 v162, v163, v162
	v_cvt_f32_u32_e32 v162, v162
	v_sub_u32_e32 v150, 32, v150
	v_ldexp_f32 v162, v162, v150
	v_fmamk_f32 v162, v162, 0x30800000, v223
	v_rsq_f32_e32 v162, v162
	v_ffbh_u32_e32 v150, v165
	v_min_u32_e32 v150, 32, v150
	v_lshlrev_b64 v[164:165], v150, v[164:165]
	v_min_u32_e32 v164, 1, v164
	v_or_b32_e32 v164, v165, v164
	v_cvt_f32_u32_e32 v164, v164
	v_sub_u32_e32 v150, 32, v150
	v_ldexp_f32 v164, v164, v150
	v_fmamk_f32 v164, v164, 0x30800000, v223
	v_rsq_f32_e32 v164, v164
	v_mov_b32_e32 v172, v144
	v_mov_b32_e32 v173, v146
	v_mov_b32_e32 v236, v148
	v_mov_b32_e32 v237, v154
	v_mov_b32_e32 v238, v156
	v_mov_b32_e32 v239, v158
	v_mov_b32_e32 v230, v162
	v_mov_b32_e32 v231, v164
	v_mov_b32_e32 v254, s64
.Lsw3_cached:
	v_mov_b32_e32 v142, v160
	v_mov_b32_e32 v143, 0
	v_lshl_add_u64 v[142:143], v[142:143], 0, s[30:31]
	v_mov_b32_e32 v166, 0xbfb8aa3b
	v_mov_b32_e32 v167, 0xbfb8aa3b
	s_lshl_b32 s98, s28, 5
	s_mov_b32 s99, 0
	s_mul_i32 s100, s28, 0xa0
	s_mov_b32 s101, 0
	v_pk_mul_f32 v[120:121], v[120:121], v[172:173] op_sel_hi:[1,0]
	v_pk_mul_f32 v[122:123], v[122:123], v[172:173] op_sel_hi:[1,0]
	v_pk_mul_f32 v[112:113], v[112:113], v[172:173] op_sel_hi:[1,0]
	v_pk_mul_f32 v[114:115], v[114:115], v[172:173] op_sel_hi:[1,0]
	v_pk_mul_f32 v[124:125], v[124:125], v[172:173] op_sel_hi:[1,0]
	v_pk_mul_f32 v[126:127], v[126:127], v[172:173] op_sel_hi:[1,0]
	v_pk_mul_f32 v[116:117], v[116:117], v[172:173] op_sel_hi:[1,0]
	v_pk_mul_f32 v[118:119], v[118:119], v[172:173] op_sel_hi:[1,0]
	v_pk_mul_f32 v[156:157], v[120:121], v[166:167]
	v_pk_mul_f32 v[158:159], v[122:123], v[166:167]
	v_pk_mul_f32 v[162:163], v[112:113], v[166:167]
	v_pk_mul_f32 v[164:165], v[114:115], v[166:167]
	v_exp_f32_e32 v156, v156
	v_exp_f32_e32 v157, v157
	v_exp_f32_e32 v158, v158
	v_exp_f32_e32 v159, v159
	v_exp_f32_e32 v162, v162
	v_exp_f32_e32 v163, v163
	v_exp_f32_e32 v164, v164
	v_exp_f32_e32 v165, v165
	v_add_f32_e32 v156, 1.0, v156
	v_add_f32_e32 v157, 1.0, v157
	v_add_f32_e32 v158, 1.0, v158
	v_add_f32_e32 v159, 1.0, v159
	v_add_f32_e32 v162, 1.0, v162
	v_add_f32_e32 v163, 1.0, v163
	v_add_f32_e32 v164, 1.0, v164
	v_add_f32_e32 v165, 1.0, v165
	v_rcp_f32_e32 v156, v156
	v_rcp_f32_e32 v157, v157
	v_rcp_f32_e32 v158, v158
	v_rcp_f32_e32 v159, v159
	v_rcp_f32_e32 v162, v162
	v_rcp_f32_e32 v163, v163
	v_rcp_f32_e32 v164, v164
	v_rcp_f32_e32 v165, v165
	v_pk_mul_f32 v[120:121], v[120:121], v[156:157]
	v_pk_mul_f32 v[122:123], v[122:123], v[158:159]
; __device__ __forceinline__ unsigned cvt_pk_bf16(float lo, float hi) { unsigned r; asm volatile("v_cvt_pk_bf16_f32 %0, %1, %2" : "=v"(r) : "v"(lo), "v"(hi)); return r; }
; __device__ __forceinline__ float siluf_(float x) { return x * sigmoidf_(x); }
;     __device__ __forceinline__ void operator()(const f32x4 (&acc)[2][2][4][2], const Unit& u, int wr, int wc, int fr, int fq) const {
;     ...
;             for (int m = 0; m < 4; ++m) { const int row = row0 + ai * HALF + m * 16; bf16_t* rowp = O + (size_t)row * ldc + col0; const float rs = rsv[ai][m];
;                 f32x4 v0, v1;
; #pragma unroll
;                 for (int j = 0; j < 4; ++j) { v0[j] = siluf_(acc[ai][0][m][0][j] * rs) * (acc[ai][1][m][0][j] * rs); v1[j] = siluf_(acc[ai][0][m][1][j] * rs) * (acc[ai][1][m][1][j] * rs); }
;                 u32x4 w; w.x = cvt_pk_bf16(v0[0], v0[1]); w.y = cvt_pk_bf16(v0[2], v0[3]); w.z = cvt_pk_bf16(v1[0], v1[1]); w.w = cvt_pk_bf16(v1[2], v1[3]);
;                 *(u32x4*)rowp = w; }
	v_pk_mul_f32 v[112:113], v[112:113], v[162:163]
	v_pk_mul_f32 v[114:115], v[114:115], v[164:165]
	v_pk_mul_f32 v[120:121], v[120:121], v[124:125]
	v_pk_mul_f32 v[122:123], v[122:123], v[126:127]
	v_pk_mul_f32 v[112:113], v[112:113], v[116:117]
	v_pk_mul_f32 v[114:115], v[114:115], v[118:119]
	v_cvt_pk_bf16_f32 v120, v120, v121
	v_cvt_pk_bf16_f32 v121, v122, v123
	v_cvt_pk_bf16_f32 v122, v112, v113
	v_cvt_pk_bf16_f32 v123, v114, v115
	global_store_dwordx4 v[142:143], v[120:123], off
	v_lshl_add_u64 v[142:143], v[142:143], 0, s[98:99]
	v_pk_mul_f32 v[104:105], v[104:105], v[172:173] op_sel:[0,1]
	v_pk_mul_f32 v[106:107], v[106:107], v[172:173] op_sel:[0,1]
	v_pk_mul_f32 v[96:97], v[96:97], v[172:173] op_sel:[0,1]
	v_pk_mul_f32 v[98:99], v[98:99], v[172:173] op_sel:[0,1]
	v_pk_mul_f32 v[108:109], v[108:109], v[172:173] op_sel:[0,1]
	v_pk_mul_f32 v[110:111], v[110:111], v[172:173] op_sel:[0,1]
	v_pk_mul_f32 v[100:101], v[100:101], v[172:173] op_sel:[0,1]
	v_pk_mul_f32 v[102:103], v[102:103], v[172:173] op_sel:[0,1]
	v_pk_mul_f32 v[156:157], v[104:105], v[166:167]
	v_pk_mul_f32 v[158:159], v[106:107], v[166:167]
	v_pk_mul_f32 v[162:163], v[96:97], v[166:167]
	v_pk_mul_f32 v[164:165], v[98:99], v[166:167]
	v_exp_f32_e32 v156, v156
	v_exp_f32_e32 v157, v157
	v_exp_f32_e32 v158, v158
	v_exp_f32_e32 v159, v159
	v_exp_f32_e32 v162, v162
	v_exp_f32_e32 v163, v163
	v_exp_f32_e32 v164, v164
	v_exp_f32_e32 v165, v165
	v_add_f32_e32 v156, 1.0, v156
	v_add_f32_e32 v157, 1.0, v157
	v_add_f32_e32 v158, 1.0, v158
	v_add_f32_e32 v159, 1.0, v159
	v_add_f32_e32 v162, 1.0, v162
	v_add_f32_e32 v163, 1.0, v163
	v_add_f32_e32 v164, 1.0, v164
	v_add_f32_e32 v165, 1.0, v165
	v_rcp_f32_e32 v156, v156
	v_rcp_f32_e32 v157, v157
	v_rcp_f32_e32 v158, v158
	v_rcp_f32_e32 v159, v159
	v_rcp_f32_e32 v162, v162
	v_rcp_f32_e32 v163, v163
	v_rcp_f32_e32 v164, v164
	v_rcp_f32_e32 v165, v165
	v_pk_mul_f32 v[104:105], v[104:105], v[156:157]
	v_pk_mul_f32 v[106:107], v[106:107], v[158:159]
	v_pk_mul_f32 v[96:97], v[96:97], v[162:163]
	v_pk_mul_f32 v[98:99], v[98:99], v[164:165]
	v_pk_mul_f32 v[104:105], v[104:105], v[108:109]
	v_pk_mul_f32 v[106:107], v[106:107], v[110:111]
	v_pk_mul_f32 v[96:97], v[96:97], v[100:101]
	v_pk_mul_f32 v[98:99], v[98:99], v[102:103]
	v_cvt_pk_bf16_f32 v104, v104, v105
	v_cvt_pk_bf16_f32 v105, v106, v107
	v_cvt_pk_bf16_f32 v106, v96, v97
	v_cvt_pk_bf16_f32 v107, v98, v99
	global_store_dwordx4 v[142:143], v[104:107], off
	v_lshl_add_u64 v[142:143], v[142:143], 0, s[98:99]
	v_pk_mul_f32 v[88:89], v[88:89], v[236:237] op_sel_hi:[1,0]
	v_pk_mul_f32 v[90:91], v[90:91], v[236:237] op_sel_hi:[1,0]
	v_pk_mul_f32 v[80:81], v[80:81], v[236:237] op_sel_hi:[1,0]
	v_pk_mul_f32 v[82:83], v[82:83], v[236:237] op_sel_hi:[1,0]
	v_pk_mul_f32 v[92:93], v[92:93], v[236:237] op_sel_hi:[1,0]
	v_pk_mul_f32 v[94:95], v[94:95], v[236:237] op_sel_hi:[1,0]
	v_pk_mul_f32 v[84:85], v[84:85], v[236:237] op_sel_hi:[1,0]
	v_pk_mul_f32 v[86:87], v[86:87], v[236:237] op_sel_hi:[1,0]
	v_pk_mul_f32 v[156:157], v[88:89], v[166:167]
	v_pk_mul_f32 v[158:159], v[90:91], v[166:167]
	v_pk_mul_f32 v[162:163], v[80:81], v[166:167]
	v_pk_mul_f32 v[164:165], v[82:83], v[166:167]
	v_exp_f32_e32 v156, v156
	v_exp_f32_e32 v157, v157
	v_exp_f32_e32 v158, v158
	v_exp_f32_e32 v159, v159
	v_exp_f32_e32 v162, v162
	v_exp_f32_e32 v163, v163
	v_exp_f32_e32 v164, v164
	v_exp_f32_e32 v165, v165
	v_add_f32_e32 v156, 1.0, v156
	v_add_f32_e32 v157, 1.0, v157
	v_add_f32_e32 v158, 1.0, v158
	v_add_f32_e32 v159, 1.0, v159
	v_add_f32_e32 v162, 1.0, v162
	v_add_f32_e32 v163, 1.0, v163
	v_add_f32_e32 v164, 1.0, v164
	v_add_f32_e32 v165, 1.0, v165
	v_rcp_f32_e32 v156, v156
	v_rcp_f32_e32 v157, v157
	v_rcp_f32_e32 v158, v158
	v_rcp_f32_e32 v159, v159
	v_rcp_f32_e32 v162, v162
	v_rcp_f32_e32 v163, v163
	v_rcp_f32_e32 v164, v164
	v_rcp_f32_e32 v165, v165
	v_pk_mul_f32 v[88:89], v[88:89], v[156:157]
	v_pk_mul_f32 v[90:91], v[90:91], v[158:159]
	v_pk_mul_f32 v[80:81], v[80:81], v[162:163]
	v_pk_mul_f32 v[82:83], v[82:83], v[164:165]
	v_pk_mul_f32 v[88:89], v[88:89], v[92:93]
	v_pk_mul_f32 v[90:91], v[90:91], v[94:95]
	v_pk_mul_f32 v[80:81], v[80:81], v[84:85]
	v_pk_mul_f32 v[82:83], v[82:83], v[86:87]
	v_cvt_pk_bf16_f32 v88, v88, v89
	v_cvt_pk_bf16_f32 v89, v90, v91
	v_cvt_pk_bf16_f32 v90, v80, v81
	v_cvt_pk_bf16_f32 v91, v82, v83
	global_store_dwordx4 v[142:143], v[88:91], off
	v_lshl_add_u64 v[142:143], v[142:143], 0, s[98:99]
	v_pk_mul_f32 v[72:73], v[72:73], v[236:237] op_sel:[0,1]
	v_pk_mul_f32 v[74:75], v[74:75], v[236:237] op_sel:[0,1]
	v_pk_mul_f32 v[64:65], v[64:65], v[236:237] op_sel:[0,1]
	v_pk_mul_f32 v[66:67], v[66:67], v[236:237] op_sel:[0,1]
	v_pk_mul_f32 v[76:77], v[76:77], v[236:237] op_sel:[0,1]
	v_pk_mul_f32 v[78:79], v[78:79], v[236:237] op_sel:[0,1]
	v_pk_mul_f32 v[68:69], v[68:69], v[236:237] op_sel:[0,1]
	v_pk_mul_f32 v[70:71], v[70:71], v[236:237] op_sel:[0,1]
	v_pk_mul_f32 v[156:157], v[72:73], v[166:167]
	v_pk_mul_f32 v[158:159], v[74:75], v[166:167]
	v_pk_mul_f32 v[162:163], v[64:65], v[166:167]
	v_pk_mul_f32 v[164:165], v[66:67], v[166:167]
	v_exp_f32_e32 v156, v156
	v_exp_f32_e32 v157, v157
	v_exp_f32_e32 v158, v158
	v_exp_f32_e32 v159, v159
	v_exp_f32_e32 v162, v162
	v_exp_f32_e32 v163, v163
	v_exp_f32_e32 v164, v164
	v_exp_f32_e32 v165, v165
	v_add_f32_e32 v156, 1.0, v156
	v_add_f32_e32 v157, 1.0, v157
	v_add_f32_e32 v158, 1.0, v158
	v_add_f32_e32 v159, 1.0, v159
	v_add_f32_e32 v162, 1.0, v162
	v_add_f32_e32 v163, 1.0, v163
	v_add_f32_e32 v164, 1.0, v164
	v_add_f32_e32 v165, 1.0, v165
	v_rcp_f32_e32 v156, v156
	v_rcp_f32_e32 v157, v157
	v_rcp_f32_e32 v158, v158
	v_rcp_f32_e32 v159, v159
; __device__ __forceinline__ unsigned cvt_pk_bf16(float lo, float hi) { unsigned r; asm volatile("v_cvt_pk_bf16_f32 %0, %1, %2" : "=v"(r) : "v"(lo), "v"(hi)); return r; }
; __device__ __forceinline__ float siluf_(float x) { return x * sigmoidf_(x); }
;     __device__ __forceinline__ void operator()(const f32x4 (&acc)[2][2][4][2], const Unit& u, int wr, int wc, int fr, int fq) const {
;     ...
;             for (int m = 0; m < 4; ++m) { const int row = row0 + ai * HALF + m * 16; bf16_t* rowp = O + (size_t)row * ldc + col0; const float rs = rsv[ai][m];
;                 f32x4 v0, v1;
; #pragma unroll
;                 for (int j = 0; j < 4; ++j) { v0[j] = siluf_(acc[ai][0][m][0][j] * rs) * (acc[ai][1][m][0][j] * rs); v1[j] = siluf_(acc[ai][0][m][1][j] * rs) * (acc[ai][1][m][1][j] * rs); }
;                 u32x4 w; w.x = cvt_pk_bf16(v0[0], v0[1]); w.y = cvt_pk_bf16(v0[2], v0[3]); w.z = cvt_pk_bf16(v1[0], v1[1]); w.w = cvt_pk_bf16(v1[2], v1[3]);
;                 *(u32x4*)rowp = w; }
	v_rcp_f32_e32 v162, v162
	v_rcp_f32_e32 v163, v163
	v_rcp_f32_e32 v164, v164
	v_rcp_f32_e32 v165, v165
	v_pk_mul_f32 v[72:73], v[72:73], v[156:157]
	v_pk_mul_f32 v[74:75], v[74:75], v[158:159]
	v_pk_mul_f32 v[64:65], v[64:65], v[162:163]
	v_pk_mul_f32 v[66:67], v[66:67], v[164:165]
	v_pk_mul_f32 v[72:73], v[72:73], v[76:77]
	v_pk_mul_f32 v[74:75], v[74:75], v[78:79]
	v_pk_mul_f32 v[64:65], v[64:65], v[68:69]
	v_pk_mul_f32 v[66:67], v[66:67], v[70:71]
	v_cvt_pk_bf16_f32 v72, v72, v73
	v_cvt_pk_bf16_f32 v73, v74, v75
	v_cvt_pk_bf16_f32 v74, v64, v65
	v_cvt_pk_bf16_f32 v75, v66, v67
	global_store_dwordx4 v[142:143], v[72:75], off
	v_lshl_add_u64 v[142:143], v[142:143], 0, s[100:101]
	v_pk_mul_f32 v[56:57], v[56:57], v[238:239] op_sel_hi:[1,0]
	v_pk_mul_f32 v[58:59], v[58:59], v[238:239] op_sel_hi:[1,0]
	v_pk_mul_f32 v[48:49], v[48:49], v[238:239] op_sel_hi:[1,0]
	v_pk_mul_f32 v[50:51], v[50:51], v[238:239] op_sel_hi:[1,0]
	v_pk_mul_f32 v[60:61], v[60:61], v[238:239] op_sel_hi:[1,0]
	v_pk_mul_f32 v[62:63], v[62:63], v[238:239] op_sel_hi:[1,0]
	v_pk_mul_f32 v[52:53], v[52:53], v[238:239] op_sel_hi:[1,0]
	v_pk_mul_f32 v[54:55], v[54:55], v[238:239] op_sel_hi:[1,0]
	v_pk_mul_f32 v[156:157], v[56:57], v[166:167]
	v_pk_mul_f32 v[158:159], v[58:59], v[166:167]
	v_pk_mul_f32 v[162:163], v[48:49], v[166:167]
	v_pk_mul_f32 v[164:165], v[50:51], v[166:167]
	v_exp_f32_e32 v156, v156
	v_exp_f32_e32 v157, v157
	v_exp_f32_e32 v158, v158
	v_exp_f32_e32 v159, v159
	v_exp_f32_e32 v162, v162
	v_exp_f32_e32 v163, v163
	v_exp_f32_e32 v164, v164
	v_exp_f32_e32 v165, v165
	v_add_f32_e32 v156, 1.0, v156
	v_add_f32_e32 v157, 1.0, v157
	v_add_f32_e32 v158, 1.0, v158
	v_add_f32_e32 v159, 1.0, v159
	v_add_f32_e32 v162, 1.0, v162
	v_add_f32_e32 v163, 1.0, v163
	v_add_f32_e32 v164, 1.0, v164
	v_add_f32_e32 v165, 1.0, v165
	v_rcp_f32_e32 v156, v156
	v_rcp_f32_e32 v157, v157
	v_rcp_f32_e32 v158, v158
	v_rcp_f32_e32 v159, v159
	v_rcp_f32_e32 v162, v162
	v_rcp_f32_e32 v163, v163
	v_rcp_f32_e32 v164, v164
	v_rcp_f32_e32 v165, v165
	v_pk_mul_f32 v[56:57], v[56:57], v[156:157]
	v_pk_mul_f32 v[58:59], v[58:59], v[158:159]
	v_pk_mul_f32 v[48:49], v[48:49], v[162:163]
	v_pk_mul_f32 v[50:51], v[50:51], v[164:165]
	v_pk_mul_f32 v[56:57], v[56:57], v[60:61]
	v_pk_mul_f32 v[58:59], v[58:59], v[62:63]
	v_pk_mul_f32 v[48:49], v[48:49], v[52:53]
	v_pk_mul_f32 v[50:51], v[50:51], v[54:55]
	v_cvt_pk_bf16_f32 v56, v56, v57
	v_cvt_pk_bf16_f32 v57, v58, v59
	v_cvt_pk_bf16_f32 v58, v48, v49
	v_cvt_pk_bf16_f32 v59, v50, v51
	global_store_dwordx4 v[142:143], v[56:59], off
	v_lshl_add_u64 v[142:143], v[142:143], 0, s[98:99]
	v_pk_mul_f32 v[40:41], v[40:41], v[238:239] op_sel:[0,1]
	v_pk_mul_f32 v[42:43], v[42:43], v[238:239] op_sel:[0,1]
	v_pk_mul_f32 v[32:33], v[32:33], v[238:239] op_sel:[0,1]
	v_pk_mul_f32 v[34:35], v[34:35], v[238:239] op_sel:[0,1]
	v_pk_mul_f32 v[44:45], v[44:45], v[238:239] op_sel:[0,1]
	v_pk_mul_f32 v[46:47], v[46:47], v[238:239] op_sel:[0,1]
	v_pk_mul_f32 v[36:37], v[36:37], v[238:239] op_sel:[0,1]
	v_pk_mul_f32 v[38:39], v[38:39], v[238:239] op_sel:[0,1]
	v_pk_mul_f32 v[156:157], v[40:41], v[166:167]
	v_pk_mul_f32 v[158:159], v[42:43], v[166:167]
	v_pk_mul_f32 v[162:163], v[32:33], v[166:167]
	v_pk_mul_f32 v[164:165], v[34:35], v[166:167]
	v_exp_f32_e32 v156, v156
	v_exp_f32_e32 v157, v157
	v_exp_f32_e32 v158, v158
	v_exp_f32_e32 v159, v159
	v_exp_f32_e32 v162, v162
	v_exp_f32_e32 v163, v163
	v_exp_f32_e32 v164, v164
	v_exp_f32_e32 v165, v165
	v_add_f32_e32 v156, 1.0, v156
	v_add_f32_e32 v157, 1.0, v157
	v_add_f32_e32 v158, 1.0, v158
	v_add_f32_e32 v159, 1.0, v159
	v_add_f32_e32 v162, 1.0, v162
	v_add_f32_e32 v163, 1.0, v163
	v_add_f32_e32 v164, 1.0, v164
	v_add_f32_e32 v165, 1.0, v165
	v_rcp_f32_e32 v156, v156
	v_rcp_f32_e32 v157, v157
	v_rcp_f32_e32 v158, v158
	v_rcp_f32_e32 v159, v159
	v_rcp_f32_e32 v162, v162
	v_rcp_f32_e32 v163, v163
	v_rcp_f32_e32 v164, v164
	v_rcp_f32_e32 v165, v165
	v_pk_mul_f32 v[40:41], v[40:41], v[156:157]
	v_pk_mul_f32 v[42:43], v[42:43], v[158:159]
	v_pk_mul_f32 v[32:33], v[32:33], v[162:163]
	v_pk_mul_f32 v[34:35], v[34:35], v[164:165]
	v_pk_mul_f32 v[40:41], v[40:41], v[44:45]
	v_pk_mul_f32 v[42:43], v[42:43], v[46:47]
	v_pk_mul_f32 v[32:33], v[32:33], v[36:37]
	v_pk_mul_f32 v[34:35], v[34:35], v[38:39]
	v_cvt_pk_bf16_f32 v40, v40, v41
	v_cvt_pk_bf16_f32 v41, v42, v43
	v_cvt_pk_bf16_f32 v42, v32, v33
; __device__ __forceinline__ unsigned cvt_pk_bf16(float lo, float hi) { unsigned r; asm volatile("v_cvt_pk_bf16_f32 %0, %1, %2" : "=v"(r) : "v"(lo), "v"(hi)); return r; }
; __device__ __forceinline__ float siluf_(float x) { return x * sigmoidf_(x); }
;     __device__ __forceinline__ void operator()(const f32x4 (&acc)[2][2][4][2], const Unit& u, int wr, int wc, int fr, int fq) const {
;     ...
;             for (int m = 0; m < 4; ++m) { const int row = row0 + ai * HALF + m * 16; bf16_t* rowp = O + (size_t)row * ldc + col0; const float rs = rsv[ai][m];
;                 f32x4 v0, v1;
; #pragma unroll
;                 for (int j = 0; j < 4; ++j) { v0[j] = siluf_(acc[ai][0][m][0][j] * rs) * (acc[ai][1][m][0][j] * rs); v1[j] = siluf_(acc[ai][0][m][1][j] * rs) * (acc[ai][1][m][1][j] * rs); }
;                 u32x4 w; w.x = cvt_pk_bf16(v0[0], v0[1]); w.y = cvt_pk_bf16(v0[2], v0[3]); w.z = cvt_pk_bf16(v1[0], v1[1]); w.w = cvt_pk_bf16(v1[2], v1[3]);
;                 *(u32x4*)rowp = w; }
	v_cvt_pk_bf16_f32 v43, v34, v35
	global_store_dwordx4 v[142:143], v[40:43], off
	v_lshl_add_u64 v[142:143], v[142:143], 0, s[98:99]
	v_pk_mul_f32 v[24:25], v[24:25], v[230:231] op_sel_hi:[1,0]
	v_pk_mul_f32 v[26:27], v[26:27], v[230:231] op_sel_hi:[1,0]
	v_pk_mul_f32 v[16:17], v[16:17], v[230:231] op_sel_hi:[1,0]
	v_pk_mul_f32 v[18:19], v[18:19], v[230:231] op_sel_hi:[1,0]
	v_pk_mul_f32 v[28:29], v[28:29], v[230:231] op_sel_hi:[1,0]
	v_pk_mul_f32 v[30:31], v[30:31], v[230:231] op_sel_hi:[1,0]
	v_pk_mul_f32 v[20:21], v[20:21], v[230:231] op_sel_hi:[1,0]
	v_pk_mul_f32 v[22:23], v[22:23], v[230:231] op_sel_hi:[1,0]
	v_pk_mul_f32 v[156:157], v[24:25], v[166:167]
	v_pk_mul_f32 v[158:159], v[26:27], v[166:167]
	v_pk_mul_f32 v[162:163], v[16:17], v[166:167]
	v_pk_mul_f32 v[164:165], v[18:19], v[166:167]
	v_exp_f32_e32 v156, v156
	v_exp_f32_e32 v157, v157
	v_exp_f32_e32 v158, v158
	v_exp_f32_e32 v159, v159
	v_exp_f32_e32 v162, v162
	v_exp_f32_e32 v163, v163
	v_exp_f32_e32 v164, v164
	v_exp_f32_e32 v165, v165
	v_add_f32_e32 v156, 1.0, v156
	v_add_f32_e32 v157, 1.0, v157
	v_add_f32_e32 v158, 1.0, v158
	v_add_f32_e32 v159, 1.0, v159
	v_add_f32_e32 v162, 1.0, v162
	v_add_f32_e32 v163, 1.0, v163
	v_add_f32_e32 v164, 1.0, v164
	v_add_f32_e32 v165, 1.0, v165
	v_rcp_f32_e32 v156, v156
	v_rcp_f32_e32 v157, v157
	v_rcp_f32_e32 v158, v158
	v_rcp_f32_e32 v159, v159
	v_rcp_f32_e32 v162, v162
	v_rcp_f32_e32 v163, v163
	v_rcp_f32_e32 v164, v164
	v_rcp_f32_e32 v165, v165
	v_pk_mul_f32 v[24:25], v[24:25], v[156:157]
	v_pk_mul_f32 v[26:27], v[26:27], v[158:159]
	v_pk_mul_f32 v[16:17], v[16:17], v[162:163]
	v_pk_mul_f32 v[18:19], v[18:19], v[164:165]
	v_pk_mul_f32 v[24:25], v[24:25], v[28:29]
	v_pk_mul_f32 v[26:27], v[26:27], v[30:31]
	v_pk_mul_f32 v[16:17], v[16:17], v[20:21]
	v_pk_mul_f32 v[18:19], v[18:19], v[22:23]
	v_cvt_pk_bf16_f32 v24, v24, v25
	v_cvt_pk_bf16_f32 v25, v26, v27
	v_cvt_pk_bf16_f32 v26, v16, v17
	v_cvt_pk_bf16_f32 v27, v18, v19
	global_store_dwordx4 v[142:143], v[24:27], off
	v_lshl_add_u64 v[142:143], v[142:143], 0, s[98:99]
	v_pk_mul_f32 v[8:9], v[8:9], v[230:231] op_sel:[0,1]
	v_pk_mul_f32 v[10:11], v[10:11], v[230:231] op_sel:[0,1]
	v_pk_mul_f32 v[4:5], v[4:5], v[230:231] op_sel:[0,1]
	v_pk_mul_f32 v[6:7], v[6:7], v[230:231] op_sel:[0,1]
	v_pk_mul_f32 v[12:13], v[12:13], v[230:231] op_sel:[0,1]
	v_pk_mul_f32 v[14:15], v[14:15], v[230:231] op_sel:[0,1]
	v_pk_mul_f32 v[0:1], v[0:1], v[230:231] op_sel:[0,1]
	v_pk_mul_f32 v[2:3], v[2:3], v[230:231] op_sel:[0,1]
	v_pk_mul_f32 v[156:157], v[8:9], v[166:167]
	v_pk_mul_f32 v[158:159], v[10:11], v[166:167]
	v_pk_mul_f32 v[162:163], v[4:5], v[166:167]
	v_pk_mul_f32 v[164:165], v[6:7], v[166:167]
	v_exp_f32_e32 v156, v156
	v_exp_f32_e32 v157, v157
	v_exp_f32_e32 v158, v158
	v_exp_f32_e32 v159, v159
	v_exp_f32_e32 v162, v162
	v_exp_f32_e32 v163, v163
	v_exp_f32_e32 v164, v164
	v_exp_f32_e32 v165, v165
	v_add_f32_e32 v156, 1.0, v156
	v_add_f32_e32 v157, 1.0, v157
	v_add_f32_e32 v158, 1.0, v158
	v_add_f32_e32 v159, 1.0, v159
	v_add_f32_e32 v162, 1.0, v162
	v_add_f32_e32 v163, 1.0, v163
	v_add_f32_e32 v164, 1.0, v164
	v_add_f32_e32 v165, 1.0, v165
	v_rcp_f32_e32 v156, v156
	v_rcp_f32_e32 v157, v157
	v_rcp_f32_e32 v158, v158
	v_rcp_f32_e32 v159, v159
	v_rcp_f32_e32 v162, v162
	v_rcp_f32_e32 v163, v163
	v_rcp_f32_e32 v164, v164
	v_rcp_f32_e32 v165, v165
	v_pk_mul_f32 v[8:9], v[8:9], v[156:157]
	v_pk_mul_f32 v[10:11], v[10:11], v[158:159]
	v_pk_mul_f32 v[4:5], v[4:5], v[162:163]
	v_pk_mul_f32 v[6:7], v[6:7], v[164:165]
	v_pk_mul_f32 v[8:9], v[8:9], v[12:13]
	v_pk_mul_f32 v[10:11], v[10:11], v[14:15]
	v_pk_mul_f32 v[4:5], v[4:5], v[0:1]
	v_pk_mul_f32 v[6:7], v[6:7], v[2:3]
	v_cvt_pk_bf16_f32 v8, v8, v9
	v_cvt_pk_bf16_f32 v9, v10, v11
	v_cvt_pk_bf16_f32 v10, v4, v5
	v_cvt_pk_bf16_f32 v11, v6, v7
	global_store_dwordx4 v[142:143], v[8:11], off
	s_mov_b64 s[10:11], -1
	s_and_b64 vcc, exec, s[8:9]
	s_cbranch_vccnz .LBB0_299
	s_andn2_b64 vcc, exec, s[40:41]
	s_cbranch_vccnz .LBB0_298
	s_barrier
	s_branch .LBB0_298
.LBB0_314:
	v_xor_b32_e32 v230, 2, v225
	v_xor_b32_e32 v231, 4, v225
	v_mov_b32_e32 v236, 0xf149f2ca
	v_mov_b32_e32 v238, 0xfffff
	s_waitcnt vmcnt(0)
	v_readlane_b32 s60, v255, 51
	s_mov_b32 s52, 0x30000
	s_movk_i32 s53, 0x2400
	s_mov_b32 s54, 0xf149f2ca
	s_mov_b64 s[56:57], 0x100000
	s_mov_b64 s[58:59], 0xfffff
	v_readlane_b32 s61, v255, 52
	s_barrier
